# metafuse + wtlate: weight-transposition items 1984+gw (W4 tail, W5) moved from P0 to the end of P2 (same code re-entered, static return switch)
# speedup vs baseline: 1.0061x; 1.0061x over previous
; #define LAS __attribute__((address_space(3)))
; __device__ __forceinline__ unsigned xb_add(unsigned* p, unsigned v) { return __hip_atomic_fetch_add(p, v, __ATOMIC_RELAXED, __HIP_MEMORY_SCOPE_AGENT); }
; __device__ __forceinline__ unsigned xb_xcc_id() { return (unsigned)__builtin_amdgcn_s_getreg((3 << 11) | 20) & 0xFu; }
; __device__ __forceinline__ XcdBarrier xcd_barrier_post(unsigned* bar, volatile LAS unsigned* st) {
;     XcdBarrier b; b.bar = bar; b.x = xb_xcc_id(); b.st = st;
;     if (threadIdx.x == 0) (void)xb_add(&bar[XB_XCNT(b.x)], 1u);
;     return b;
; __global__ void __launch_bounds__(NTHREADS, 2) mk_fwd(Args a) {
;     extern __shared__ __attribute__((aligned(16))) unsigned char lds_raw[];
;     cg::grid_group grid = cg::this_grid();
;     LAS unsigned char* lds = (LAS unsigned char*)lds_raw;
;     const int tid = threadIdx.x, lane = tid & 63, wave = __builtin_amdgcn_readfirstlane(tid >> 6);
;     unsigned char* ws = a.ws;
;     const int G = gridDim.x, c = blockIdx.x;
;     volatile LAS unsigned* MISC = (volatile LAS unsigned*)(lds + MISC_OFF);
;     if (tid < 32) MISC[tid] = 0u;
;     __syncthreads();
;     unsigned* barw = (unsigned*)(ws + WS_BAR);
;     XcdBarrier bar = xcd_barrier_post(barw, MISC + 8);
_Z6mk_fwd4Args:
	s_load_dwordx16 s[44:59], s[0:1], 0x80
	s_load_dword s97, s[0:1], 0xd0
	s_load_dwordx2 s[92:93], s[0:1], 0xc8
	s_add_u32 s6, s0, 0xc8
	v_and_b32_e32 v224, 0x3ff, v0
	s_addc_u32 s7, s1, 0
	v_readfirstlane_b32 s41, v224
	v_mov_b32_e32 v2, s0
	v_mov_b32_e32 v3, s1
	v_mov_b32_e32 v1, 0x23f80
	ds_write_b64 v1, v[2:3]
	s_mov_b32 s101, 0
	v_cmp_gt_u32_e32 vcc, 32, v224
	s_and_saveexec_b64 s[4:5], vcc
	v_lshl_add_u32 v1, v224, 2, 0
	v_add_u32_e32 v1, 0x23f00, v1
	v_mov_b32_e32 v2, 0
	ds_write_b32 v1, v2
	s_or_b64 exec, exec, s[4:5]
	s_load_dwordx2 s[4:5], s[0:1], 0xc0
	s_waitcnt lgkmcnt(0)
	s_barrier
	s_add_u32 s94, s58, 0xc0000
	s_getreg_b32 s3, hwreg(HW_REG_XCC_ID, 0, 4)
	s_addc_u32 s95, s59, 0
	s_and_b32 s3, s3, 15
	v_cmp_eq_u32_e64 s[24:25], 0, v224
	s_and_saveexec_b64 s[8:9], s[24:25]
	s_cbranch_execz .LBB0_5
	s_mov_b64 s[10:11], exec
	v_mbcnt_lo_u32_b32 v1, s10, 0
	v_mbcnt_hi_u32_b32 v1, s11, v1
	v_cmp_eq_u32_e32 vcc, 0, v1
	s_and_b64 s[12:13], exec, vcc
	s_mov_b64 exec, s[12:13]
	s_cbranch_execz .LBB0_5
	s_lshl_b32 s12, s3, 8
	s_bcnt1_i32_b64 s10, s[10:11]
	v_mov_b32_e32 v1, s12
	v_mov_b32_e32 v2, s10
	global_atomic_add v255, v1, v2, s[94:95] offset:1024 sc0

; __device__ __forceinline__ void transpose_item(const float* W, int ldw, const float* gk, int K, int N, bf16* WT, bool glu, LAS float* scr, int item, int lane, bool f16 = false) {
;     const int nblk = N / 64, kb = item / nblk, nb = item % nblk, k0 = 64 * kb, n0 = 64 * nb;
;     const int kq = lane >> 4, n4 = (lane & 15) * 4;
;     f32x4 v[16];
; #pragma unroll
;     for (int i = 0; i < 16; ++i) v[i] = __builtin_nontemporal_load((const f32x4*)(W + (size_t)(k0 + 4 * i + kq) * ldw + n0 + n4));
; #pragma unroll
;     for (int i = 0; i < 16; ++i) { LAS float* d = scr + (4 * i + kq) * TP + n4; d[0] = v[i].x; d[1] = v[i].y; d[2] = v[i].z; d[3] = v[i].w; }
;     LDS_WAIT(); asm volatile("" ::: "memory");
;     int d0 = n0; if (glu) { const int half = N / 2, bj = n0 / half, j = n0 % half; d0 = 256 * (j / 128) + 128 * bj + (j % 128); }
;     const int c = lane & 7;
;     float g[8];
; __device__ __forceinline__ void p0_prologue(const Args& a, LAS unsigned char* lds, int wave, int lane) {
;     unsigned char* ws = a.ws;
;     LAS float* scr = (LAS float*)(lds + wave * 16896);
;     const int gw = blockIdx.x * NWAVES + wave, NGW = gridDim.x * NWAVES;
;     constexpr int I1 = (DM / 64) * (NQKVU / 64), IG = (DM / 64) * (2048 / 64), I2 = (DM / 64) * (2048 / 64), I3 = (DM / 64) * (DM / 64), I4 = (DM / 64) * (2 * DFF / 64), I5 = (DFF / 64) * (DM / 64);
;     static_assert(T_SCR_BYTES <= 16896 && 8 * 16896 <= LDS_BYTES - 1024, "transpose scratch");
;     constexpr int NITEMS = I1 + IG + I2 + I3 + I4 + I5;
;     for (int it = gw; it < NITEMS; it += NGW) {
;         int r = it;
;         if (r < I1) { transpose_item(a.in[3], INC, a.in[2], DM, NQKVU, (bf16*)(ws + WS_W1), false, scr, r, lane); continue; } r -= I1;
;         if (r < IG) { transpose_item(a.in[3] + NQKVU, INC, a.in[2], DM, 2048, (bf16*)(ws + WS_WG), true, scr, r, lane); continue; } r -= IG;
;         if (r < I2) { transpose_item(a.in[15], 2048, nullptr, DM, 2048, (bf16*)(ws + WS_W2), true, scr, r, lane); continue; } r -= I2;
;         if (r < I3) { transpose_item(a.in[18], DM, nullptr, DM, DM, (bf16*)(ws + WS_W3), false, scr, r, lane); continue; } r -= I3;
;         if (r < I4) { transpose_item(a.in[20], 2 * DFF, a.in[19], DM, 2 * DFF, (bf16*)(ws + WS_W4), true, scr, r, lane, true); continue; } r -= I4;
;         transpose_item(a.in[21], DM, nullptr, DFF, DM, (bf16*)(ws + WS_W5), false, scr, r, lane);
;     }
.LBB0_17:
	s_load_dwordx16 s[76:91], s[0:1], 0x0
	s_load_dwordx16 s[60:75], s[0:1], 0x40
	s_lshr_b32 s33, s41, 6
	s_lshl_b32 s40, s2, 3
	s_add_i32 s38, s33, s40
	s_lshl_b32 s96, s92, 3
	v_and_b32_e32 v128, 63, v224
	s_cmpk_gt_i32 s38, 0x7bf
	v_lshlrev_b32_e32 v112, 4, v224
	v_and_b32_e32 v131, 7, v224
	s_cbranch_scc1 .LBB0_88
.Lwt_setup:
	s_mul_i32 s0, s33, 0x4200
	v_lshrrev_b32_e32 v36, 4, v128
	s_add_i32 s4, s0, 0
	v_and_b32_e32 v22, 0xf0, v112
	v_mul_u32_u24_e32 v0, 0x104, v36
	v_add3_u32 v37, s4, v22, v0
	v_lshlrev_b32_e32 v0, 4, v131
	v_mov_b32_e32 v1, 0
	v_lshrrev_b32_e32 v39, 3, v128
	v_lshl_add_u64 v[12:13], s[58:59], 0, v[0:1]
	s_mov_b64 s[0:1], 0x1c00000
	v_mul_u32_u24_e32 v4, 0x820, v131
	v_lshl_add_u64 v[2:3], v[12:13], 0, s[0:1]
	v_lshlrev_b32_e32 v0, 2, v39
	s_mov_b64 s[0:1], 0x1100000
	v_add3_u32 v40, s4, v4, v0
	v_lshl_add_u64 v[4:5], v[12:13], 0, s[0:1]
	s_mov_b64 s[0:1], 0xf00000
	v_lshl_add_u64 v[6:7], v[12:13], 0, s[0:1]
	s_mov_b64 s[0:1], 0xb00000
	v_lshl_add_u64 v[8:9], v[12:13], 0, s[0:1]
	s_mov_b64 s[0:1], 0x700000
	v_lshl_add_u64 v[10:11], v[12:13], 0, s[0:1]
	s_mov_b64 s[0:1], 0x200000
	v_mov_b32_e32 v23, v1
	s_cmp_lg_u64 s[50:51], 0
	v_lshl_add_u64 v[12:13], v[12:13], 0, s[0:1]
	v_lshl_add_u64 v[14:15], s[54:55], 0, v[22:23]
	v_lshl_add_u64 v[16:17], s[52:53], 0, v[22:23]
	v_lshl_add_u64 v[18:19], s[48:49], 0, v[22:23]
	s_waitcnt lgkmcnt(0)
	v_lshl_add_u64 v[20:21], s[74:75], 0, v[22:23]
	v_lshl_add_u64 v[22:23], s[82:83], 0, v[22:23]
	s_cselect_b64 s[4:5], -1, 0
	s_mov_b64 s[0:1], 0x2800
	s_cmp_lg_u64 s[80:81], 0
	v_lshl_add_u64 v[24:25], v[22:23], 0, s[0:1]
	s_cselect_b64 s[6:7], -1, 0
	s_lshl_b32 s0, s38, 1
	v_lshlrev_b32_e32 v38, 3, v131
	v_or_b32_e32 v41, 8, v39
	v_or_b32_e32 v42, 16, v39
	v_or_b32_e32 v43, 24, v39
	v_or_b32_e32 v44, 32, v39
	v_or_b32_e32 v45, 40, v39
	v_or_b32_e32 v46, 48, v39
	v_or_b32_e32 v47, 56, v39
	s_lshl_b32 s14, s38, 6
	s_lshl_b32 s15, s92, 9
	s_lshl_b32 s16, s38, 2
	s_lshl_b32 s17, s92, 5
	s_add_i32 s18, s0, 0x1f700
	s_lshl_b32 s19, s92, 4
	s_lshl_b32 s20, s38, 3
	s_lshl_b32 s21, s92, 6
	s_mov_b32 s22, 0x24000
	s_mov_b32 s23, 0x2c000
	v_add_u32_e32 v48, 0x410, v37
	v_add_u32_e32 v49, 0x418, v37
	v_add_u32_e32 v50, 0x820, v37
	v_add_u32_e32 v51, 0x828, v37
	v_add_u32_e32 v52, 0xc30, v37
	v_add_u32_e32 v53, 0xc38, v37
	v_add_u32_e32 v54, 0x1040, v37
	v_add_u32_e32 v55, 0x1048, v37
	v_add_u32_e32 v56, 0x1450, v37
	v_add_u32_e32 v57, 0x1458, v37
	v_add_u32_e32 v58, 0x1860, v37
	v_add_u32_e32 v59, 0x1868, v37
	v_add_u32_e32 v60, 0x1c70, v37
	v_add_u32_e32 v61, 0x1c78, v37
	v_add_u32_e32 v62, 0x2080, v37
	v_add_u32_e32 v63, 0x2088, v37
	v_add_u32_e32 v64, 0x2490, v37
	s_mov_b32 s52, 0x16000
	s_mov_b32 s53, 0x42000
	s_mov_b32 s26, 0x58000
	s_mov_b32 s27, 0x6e000
	s_mov_b32 s28, 0x84000
	s_mov_b32 s29, 0x9a000
	s_mov_b32 s30, 0xb0000
	s_mov_b32 s31, 0xc6000
	s_mov_b32 s34, 0xdc000
	v_add_u32_e32 v65, 0x2498, v37
	v_mov_b32_e32 v66, 0x200
	s_mov_b32 s35, 0xf2000
	s_mov_b32 s36, 0x108000
	s_mov_b32 s37, 0x11e000
	s_mov_b32 s39, 0x134000
	s_mov_b32 s42, 0x14a000
	s_mov_b32 s43, 0x48000
	s_movk_i32 s48, 0x4800
	s_mov_b32 s49, s38
	s_mov_b32 s9, 0
	s_branch .LBB0_21

; __device__ __forceinline__ void p0_prologue(const Args& a, LAS unsigned char* lds, int wave, int lane) {
;     ...
;     for (int it = gw; it < NITEMS; it += NGW) {
;         int r = it;
;         if (r < I1) { transpose_item(a.in[3], INC, a.in[2], DM, NQKVU, (bf16*)(ws + WS_W1), false, scr, r, lane); continue; } r -= I1;
;         if (r < IG) { transpose_item(a.in[3] + NQKVU, INC, a.in[2], DM, 2048, (bf16*)(ws + WS_WG), true, scr, r, lane); continue; } r -= IG;
;         if (r < I2) { transpose_item(a.in[15], 2048, nullptr, DM, 2048, (bf16*)(ws + WS_W2), true, scr, r, lane); continue; } r -= I2;
;         if (r < I3) { transpose_item(a.in[18], DM, nullptr, DM, DM, (bf16*)(ws + WS_W3), false, scr, r, lane); continue; } r -= I3;
;         if (r < I4) { transpose_item(a.in[20], 2 * DFF, a.in[19], DM, 2 * DFF, (bf16*)(ws + WS_W4), true, scr, r, lane, true); continue; } r -= I4;
;         transpose_item(a.in[21], DM, nullptr, DFF, DM, (bf16*)(ws + WS_W5), false, scr, r, lane);
;     }
.LBB0_20:
	s_add_i32 s49, s49, s96
	s_add_i32 s14, s14, s15
	s_add_i32 s16, s16, s17
	s_add_i32 s18, s18, s19
	s_add_i32 s20, s20, s21
	s_cmpk_gt_i32 s49, 0x7bf
	s_cbranch_scc0 .LBB0_21
	s_cmp_lg_u32 s101, 0
	s_cbranch_scc1 .Lwt_ret
	s_branch .LBB0_88

; __device__ __forceinline__ unsigned xb_ld(unsigned* p)              { return __hip_atomic_load(p, __ATOMIC_RELAXED, __HIP_MEMORY_SCOPE_AGENT); }
; __device__ __forceinline__ void xcd_barrier_complete(unsigned* bar, unsigned x, unsigned& nloc, unsigned& nx) {
;     const unsigned G = gridDim.x * gridDim.y * gridDim.z;
;     unsigned sum, cnt, mine, sp = 0u;
;     for (;;) {
;         sum = 0u; cnt = 0u; mine = 0u;
; #pragma unroll
;         for (unsigned j = 0; j < 16; ++j) { const unsigned c = xb_ld(&bar[XB_XCNT(j)]); sum += c; cnt += (c > 0u) ? 1u : 0u; mine = (j == x) ? c : mine; }
; __device__ __forceinline__ void xcd_barrier(const XcdBarrier& b) {
;     asm volatile("s_waitcnt vmcnt(0)" ::: "memory");
;     __syncthreads();
;     if (threadIdx.x == 0) {
;         unsigned* bar = b.bar;
;         __builtin_amdgcn_s_waitcnt(0);
;         unsigned nloc = b.st[0], nx = b.st[1];
;         if (nloc == 0u) { xcd_barrier_complete(bar, b.x, nloc, nx); b.st[0] = nloc; b.st[1] = nx; }
.LBB0_274:
	s_barrier
	v_mov_b32_e32 v169, v104
	v_mov_b32_e32 v170, v105
	v_mov_b32_e32 v171, v116
	v_mov_b32_e32 v172, s48
	v_mov_b32_e32 v173, s49
	v_mov_b32_e32 v174, s50
	v_mov_b32_e32 v175, s51
	v_mov_b32_e32 v176, s52
	v_mov_b32_e32 v177, s53
	v_mov_b32_e32 v178, s54
	v_mov_b32_e32 v179, s55
	v_mov_b32_e32 v0, 0x23f80
	ds_read_b64 v[0:1], v0
	s_waitcnt lgkmcnt(0)
	v_readfirstlane_b32 s4, v0
	v_readfirstlane_b32 s5, v1
	s_load_dwordx8 s[48:55], s[4:5], 0x90
	s_load_dwordx2 s[74:75], s[4:5], 0x78
	s_load_dwordx4 s[80:83], s[4:5], 0x10
	s_add_i32 s38, s33, s40
	s_addk_i32 s38, 0x7c0
	v_lshlrev_b32_e32 v112, 4, v224
	v_and_b32_e32 v131, 7, v224
	s_mov_b32 s101, 1
	s_waitcnt lgkmcnt(0)
	s_branch .Lwt_setup
.Lwt_ret:
	v_mov_b32_e32 v104, v169
	v_mov_b32_e32 v105, v170
	v_mov_b32_e32 v116, v171
	v_readfirstlane_b32 s48, v172
	v_readfirstlane_b32 s49, v173
	v_readfirstlane_b32 s50, v174
	v_readfirstlane_b32 s51, v175
	v_readfirstlane_b32 s52, v176
	v_readfirstlane_b32 s53, v177
	v_readfirstlane_b32 s54, v178
	v_readfirstlane_b32 s55, v179
	s_waitcnt vmcnt(0)
	s_barrier
	s_and_saveexec_b64 s[0:1], s[90:91]
	s_cbranch_execz .LBB0_326
	s_add_i32 s4, 0, 0x23f20
	v_mov_b32_e32 v0, s4
	s_waitcnt vmcnt(0) expcnt(0) lgkmcnt(0)
	ds_read_b32 v2, v0
	s_add_i32 s4, 0, 0x23f24
	v_mov_b32_e32 v0, s4
	ds_read_b32 v0, v0
	s_waitcnt lgkmcnt(1)
	v_cmp_ne_u32_e32 vcc, 0, v2
	s_cbranch_vccnz .LBB0_290
	s_add_u32 s4, s58, 0xc0200
	s_addc_u32 s5, s59, 0
	s_add_u32 s6, s58, 0xc0400
	s_addc_u32 s7, s59, 0
	s_add_u32 s8, s58, 0xc0500
	s_addc_u32 s9, s59, 0
	s_add_u32 s10, s58, 0xc0600
	s_addc_u32 s11, s59, 0
	s_add_u32 s12, s58, 0xc0700
	s_addc_u32 s13, s59, 0
	s_add_u32 s14, s58, 0xc0800
	s_addc_u32 s15, s59, 0
	s_add_u32 s16, s58, 0xc0900
	s_addc_u32 s17, s59, 0
	s_add_u32 s18, s58, 0xc0a00
	s_addc_u32 s19, s59, 0
	s_add_u32 s20, s58, 0xc0b00
	s_addc_u32 s21, s59, 0
	s_add_u32 s22, s58, 0xc0c00
	s_addc_u32 s23, s59, 0
	s_add_u32 s24, s58, 0xc0d00
	s_addc_u32 s25, s59, 0
	s_add_u32 s26, s58, 0xc0e00
	s_addc_u32 s27, s59, 0
	s_add_u32 s28, s58, 0xc0f00
	s_addc_u32 s29, s59, 0
	s_add_u32 s30, s58, 0xc1000
	s_addc_u32 s31, s59, 0
	s_add_u32 s34, s58, 0xc1100
	s_addc_u32 s35, s59, 0
	s_add_u32 s36, s58, 0xc1200
	s_addc_u32 s37, s59, 0
	s_mul_i32 s41, s93, s97
	s_add_u32 s38, s58, 0xc1300
	s_mul_i32 s41, s41, s92
	s_addc_u32 s39, s59, 0
	s_mov_b32 s66, 1
	v_mov_b32_e32 v16, 0
	s_branch .LBB0_278
